# LRU gate tail: cross-half exchange of scan aggregates via v_permlane32_swap_b32 instead of two ds_bpermute_b32 LDS round trips
# speedup vs baseline: 1.0123x; 1.0019x over previous
; #define LAS __attribute__((address_space(3)))
; template <int dir>
; __device__ __forceinline__ void lru_pass(LAS unsigned char* lds, const Params& P, int b, int h, int q, bool dry) {
;     ...
;             { const int sl = 32 * wid + s_i; const int tlA = dir == 0 ? sl : 255 - sl;
;               const LAS unsigned char* ap = XC + tlA * XC_PITCH + 16 * g;
;               const LAS unsigned char* wrp = WB + nl * XC_PITCH + 16 * g; const LAS unsigned char* wip = wrp + 32 * XC_PITCH;
; #pragma unroll
;               for (int ks = 0; ks < 8; ++ks) { const bf16x8 A = *(const LAS bf16x8*)(ap + 32 * ks);
;                   const bf16x8 Br = *(const LAS bf16x8*)(wrp + 32 * ks), Bi = *(const LAS bf16x8*)(wip + 32 * ks);
;                   zr = __builtin_amdgcn_mfma_f32_32x32x16_bf16(A, Br, zr, 0, 0, 0); zi = __builtin_amdgcn_mfma_f32_32x32x16_bf16(A, Bi, zi, 0, 0, 0); } }
;             unsigned xcb[16], pk[16];
; #pragma unroll
;             for (int v = 0; v < 16; ++v) { const int s = sbase + v; const int tl = dir == 0 ? s : 255 - s; xcb[v] = *(const LAS bf16_t*)(XC + tl * XC_PITCH + chl * 2);
;                 if (dir == 0) pk[v] = *(const LAS bf16_t*)(TIN + tl * IO_NP + nl * 2); else pk[v] = *(const LAS unsigned*)(TIN + tl * IO_WP + nl * 4); }
;             float Pp = 1.f, E = 0.f;
; #pragma unroll
;             for (int v = 0; v < 16; ++v) {
;                 const float xcv = __uint_as_float(xcb[v] << 16);
;                 const float r = __builtin_amdgcn_rcpf(1.0f + __builtin_amdgcn_exp2f(zr[v]));
;                 const float ig = __builtin_amdgcn_rcpf(1.0f + __builtin_amdgcn_exp2f(zi[v]));
;                 const float a = __builtin_amdgcn_exp2f(cl * r);
;                 const float sq = __builtin_amdgcn_sqrtf(fmaf(-a, a, 1.0f));
;                 const float u = sq * ig * xcv;
;                 E = fmaf(a, E, u); Pp *= a; zr[v] = E; zi[v] = Pp; }
.Llruf_wres:
	ds_read_b128 v[120:123], v160
	ds_read_b128 v[124:127], v160 offset:32
	ds_read_b128 v[168:171], v160 offset:64
	ds_read_b128 v[172:175], v160 offset:96
	ds_read_b128 v[176:179], v160 offset:128
	ds_read_b128 v[180:183], v160 offset:160
	ds_read_b128 v[184:187], v160 offset:192
	ds_read_b128 v[188:191], v160 offset:224
	ds_read_b128 v[236:239], v161 offset:8704
	ds_read_b128 v[240:243], v161 offset:8736
	ds_read_b128 v[244:247], v161 offset:8768
	ds_read_b128 v[248:251], v161 offset:8800
	s_waitcnt lgkmcnt(11)
	v_mfma_f32_32x32x16_bf16 v[32:47], v[120:123], v[204:207], v[0:15]
	s_waitcnt lgkmcnt(10)
	v_mfma_f32_32x32x16_bf16 v[32:47], v[124:127], v[208:211], v[32:47]
	s_waitcnt lgkmcnt(9)
	v_mfma_f32_32x32x16_bf16 v[32:47], v[168:171], v[212:215], v[32:47]
	s_waitcnt lgkmcnt(8)
	v_mfma_f32_32x32x16_bf16 v[32:47], v[172:175], v[216:219], v[32:47]
	s_waitcnt lgkmcnt(7)
	v_mfma_f32_32x32x16_bf16 v[32:47], v[176:179], v[220:223], v[32:47]
	s_waitcnt lgkmcnt(6)
	v_mfma_f32_32x32x16_bf16 v[32:47], v[180:183], v[224:227], v[32:47]
	s_waitcnt lgkmcnt(5)
	v_mfma_f32_32x32x16_bf16 v[32:47], v[184:187], v[228:231], v[32:47]
	s_waitcnt lgkmcnt(4)
	v_mfma_f32_32x32x16_bf16 v[32:47], v[188:191], v[232:235], v[32:47]
	s_waitcnt lgkmcnt(3)
	v_mfma_f32_32x32x16_bf16 v[48:63], v[120:123], v[236:239], v[16:31]
	ds_read_b128 v[236:239], v161 offset:8832
	s_nop 8
	v_exp_f32_e32 v32, v32
	v_exp_f32_e32 v33, v33
	v_exp_f32_e32 v34, v34
	v_add_f32_e32 v32, 1.0, v32
	v_rcp_f32_e32 v32, v32
	s_waitcnt lgkmcnt(3)
	v_mfma_f32_32x32x16_bf16 v[48:63], v[124:127], v[240:243], v[48:63]
	ds_read_b128 v[240:243], v161 offset:8864
	v_add_f32_e32 v33, 1.0, v33
	v_mul_f32_e32 v32, v138, v32
	v_rcp_f32_e32 v33, v33
	s_nop 0
	v_mul_f32_e32 v33, v138, v33
	s_waitcnt lgkmcnt(3)
	v_mfma_f32_32x32x16_bf16 v[48:63], v[168:171], v[244:247], v[48:63]
	ds_read_b128 v[244:247], v161 offset:8896
	v_exp_f32_e32 v33, v33
	s_waitcnt lgkmcnt(3)
	v_mfma_f32_32x32x16_bf16 v[48:63], v[172:175], v[248:251], v[48:63]
	ds_read_b128 v[248:251], v161 offset:8928
	ds_read_u16 v152, v162
	ds_read_u16 v154, v162 offset:272
	ds_read_u16 v155, v162 offset:544
	ds_read_u16 v157, v162 offset:816
	ds_read_u16 v196, v162 offset:1088
	ds_read_u16 v197, v162 offset:1360
	s_waitcnt lgkmcnt(5)
	v_lshlrev_b32_e32 v152, 16, v152
	s_waitcnt lgkmcnt(4)
	v_lshlrev_b32_e32 v154, 16, v154
	v_mfma_f32_32x32x16_bf16 v[48:63], v[176:179], v[236:239], v[48:63]
	ds_read_u16 v177, v162 offset:1632
	ds_read_u16 v178, v162 offset:1904
	ds_read_u16 v127, v163
	ds_read_u16 v124, v163 offset:80
	ds_read_u16 v121, v163 offset:160
	ds_read_u16 v66, v163 offset:240
	ds_read_u16 v64, v163 offset:320
	ds_read_u16 v126, v163 offset:400
	ds_read_u16 v123, v163 offset:480
	ds_read_u16 v120, v163 offset:560
	v_mfma_f32_32x32x16_bf16 v[48:63], v[180:183], v[240:243], v[48:63]
	v_exp_f32_e32 v171, v32
	ds_read_u16 v179, v162 offset:2176
	ds_read_u16 v180, v162 offset:2448
	ds_read_u16 v181, v162 offset:2720
	v_mfma_f32_32x32x16_bf16 v[48:63], v[184:187], v[244:247], v[48:63]
	ds_read_u16 v182, v162 offset:2992
	ds_read_u16 v183, v162 offset:3264
	ds_read_u16 v184, v162 offset:3536
	ds_read_u16 v185, v162 offset:3808
	ds_read_u16 v187, v162 offset:4080
	v_mfma_f32_32x32x16_bf16 v[48:63], v[188:191], v[248:251], v[48:63]
	s_nop 11
	v_exp_f32_e32 v172, v48
	ds_read_u16 v170, v163 offset:640
	ds_read_u16 v169, v163 offset:720
	ds_read_u16 v168, v163 offset:800
	ds_read_u16 v166, v163 offset:880
	ds_read_u16 v125, v163 offset:960
	ds_read_u16 v122, v163 offset:1040
	ds_read_u16 v67, v163 offset:1120
	ds_read_u16 v48, v163 offset:1200
	v_add_f32_e32 v32, 1.0, v172
	v_fma_f32 v172, -v171, v171, 1.0
	v_rcp_f32_e32 v32, v32
	v_sqrt_f32_e32 v172, v172
	s_nop 0
	v_mul_f32_e32 v32, v172, v32
	v_exp_f32_e32 v172, v49
	v_mul_f32_e32 v49, v32, v152
	v_fma_f32 v152, -v33, v33, 1.0
	v_sqrt_f32_e32 v152, v152
	v_add_f32_e32 v32, 1.0, v172
	v_rcp_f32_e32 v32, v32
	v_fmac_f32_e32 v49, 0, v171
	v_mul_f32_e32 v32, v152, v32
	v_mul_f32_e32 v172, v32, v154
	v_add_f32_e32 v32, 1.0, v34
	v_rcp_f32_e32 v32, v32
	v_exp_f32_e32 v34, v50
	v_fmac_f32_e32 v172, v33, v49
	v_mul_f32_e32 v50, v171, v33
	v_mul_f32_e32 v32, v138, v32
	v_exp_f32_e32 v32, v32
	v_add_f32_e32 v33, 1.0, v34
	v_exp_f32_e32 v34, v35
	v_rcp_f32_e32 v33, v33
	v_fma_f32 v35, -v32, v32, 1.0
	v_sqrt_f32_e32 v35, v35
	v_add_f32_e32 v34, 1.0, v34
	v_rcp_f32_e32 v34, v34
	s_waitcnt lgkmcnt(14)
; template <int dir>
; __device__ __forceinline__ void lru_pass(LAS unsigned char* lds, const Params& P, int b, int h, int q, bool dry) {
;     ...
;             for (int v = 0; v < 16; ++v) {
;                 const float xcv = __uint_as_float(xcb[v] << 16);
;                 const float r = __builtin_amdgcn_rcpf(1.0f + __builtin_amdgcn_exp2f(zr[v]));
;                 const float ig = __builtin_amdgcn_rcpf(1.0f + __builtin_amdgcn_exp2f(zi[v]));
;                 const float a = __builtin_amdgcn_exp2f(cl * r);
;                 const float sq = __builtin_amdgcn_sqrtf(fmaf(-a, a, 1.0f));
;                 const float u = sq * ig * xcv;
;                 E = fmaf(a, E, u); Pp *= a; zr[v] = E; zi[v] = Pp; }
;             const float Po = __shfl_xor(Pp, 32), Eo = __shfl_xor(E, 32);
;             const float P0 = g ? Po : Pp, E0 = g ? Eo : E, P1 = g ? Pp : Po, E1 = g ? E : Eo;
;             if (g == 0) { AGG[(wid * 2 + 0) * 32 + nl] = P0 * P1; AGG[(wid * 2 + 1) * 32 + nl] = fmaf(P1, E0, E1); }
	v_lshlrev_b32_e32 v152, 16, v155
	v_mul_f32_e32 v33, v35, v33
	v_mul_f32_e32 v173, v33, v152
	v_mul_f32_e32 v34, v138, v34
	v_exp_f32_e32 v33, v51
	v_exp_f32_e32 v34, v34
	v_fmac_f32_e32 v173, v32, v172
	v_mul_f32_e32 v51, v32, v50
	v_exp_f32_e32 v32, v36
	v_add_f32_e32 v33, 1.0, v33
	v_fma_f32 v35, -v34, v34, 1.0
	v_rcp_f32_e32 v33, v33
	v_sqrt_f32_e32 v35, v35
	v_add_f32_e32 v32, 1.0, v32
	v_rcp_f32_e32 v32, v32
	v_lshlrev_b32_e32 v36, 16, v157
	v_mul_f32_e32 v33, v35, v33
	v_mul_f32_e32 v174, v33, v36
	v_mul_f32_e32 v32, v138, v32
	v_fmac_f32_e32 v174, v34, v173
	v_exp_f32_e32 v33, v52
	v_mul_f32_e32 v52, v34, v51
	v_exp_f32_e32 v32, v32
	v_exp_f32_e32 v34, v37
	v_add_f32_e32 v33, 1.0, v33
	v_rcp_f32_e32 v33, v33
	v_fma_f32 v35, -v32, v32, 1.0
	v_add_f32_e32 v34, 1.0, v34
	v_sqrt_f32_e32 v35, v35
	v_rcp_f32_e32 v34, v34
	v_lshlrev_b32_e32 v36, 16, v196
	v_mul_f32_e32 v33, v35, v33
	v_mul_f32_e32 v34, v138, v34
	v_mul_f32_e32 v175, v33, v36
	v_exp_f32_e32 v33, v53
	v_exp_f32_e32 v34, v34
	v_fmac_f32_e32 v175, v32, v174
	v_mul_f32_e32 v53, v32, v52
	v_exp_f32_e32 v32, v38
	v_add_f32_e32 v33, 1.0, v33
	v_fma_f32 v35, -v34, v34, 1.0
	v_rcp_f32_e32 v33, v33
	v_sqrt_f32_e32 v35, v35
	v_add_f32_e32 v32, 1.0, v32
	v_rcp_f32_e32 v32, v32
	v_lshlrev_b32_e32 v36, 16, v197
	v_mul_f32_e32 v33, v35, v33
	v_mul_f32_e32 v176, v33, v36
	v_mul_f32_e32 v32, v138, v32
	v_fmac_f32_e32 v176, v34, v175
	v_exp_f32_e32 v33, v54
	v_mul_f32_e32 v54, v34, v53
	v_exp_f32_e32 v32, v32
	v_exp_f32_e32 v34, v39
	v_add_f32_e32 v33, 1.0, v33
	v_rcp_f32_e32 v33, v33
	v_fma_f32 v35, -v32, v32, 1.0
	v_add_f32_e32 v34, 1.0, v34
	v_sqrt_f32_e32 v35, v35
	v_rcp_f32_e32 v34, v34
	v_lshlrev_b32_e32 v36, 16, v177
	v_mul_f32_e32 v33, v35, v33
	v_mul_f32_e32 v34, v138, v34
	v_mul_f32_e32 v177, v33, v36
	v_exp_f32_e32 v33, v55
	v_exp_f32_e32 v34, v34
	v_fmac_f32_e32 v177, v32, v176
	v_mul_f32_e32 v55, v32, v54
	v_exp_f32_e32 v32, v40
	v_add_f32_e32 v33, 1.0, v33
	v_fma_f32 v35, -v34, v34, 1.0
	v_rcp_f32_e32 v33, v33
	v_sqrt_f32_e32 v35, v35
	v_add_f32_e32 v32, 1.0, v32
	v_rcp_f32_e32 v32, v32
	v_lshlrev_b32_e32 v36, 16, v178
	v_mul_f32_e32 v33, v35, v33
	v_mul_f32_e32 v178, v33, v36
	v_mul_f32_e32 v32, v138, v32
	v_fmac_f32_e32 v178, v34, v177
	v_exp_f32_e32 v33, v56
	v_mul_f32_e32 v56, v34, v55
	v_exp_f32_e32 v32, v32
	v_exp_f32_e32 v34, v41
	v_add_f32_e32 v33, 1.0, v33
	v_rcp_f32_e32 v33, v33
	v_fma_f32 v35, -v32, v32, 1.0
	v_add_f32_e32 v34, 1.0, v34
	v_sqrt_f32_e32 v35, v35
	v_rcp_f32_e32 v34, v34
	v_lshlrev_b32_e32 v36, 16, v179
	v_mul_f32_e32 v33, v35, v33
	v_mul_f32_e32 v34, v138, v34
	v_mul_f32_e32 v179, v33, v36
	v_exp_f32_e32 v33, v57
	v_exp_f32_e32 v34, v34
	v_fmac_f32_e32 v179, v32, v178
	v_mul_f32_e32 v57, v32, v56
	v_exp_f32_e32 v32, v42
	v_add_f32_e32 v33, 1.0, v33
	v_fma_f32 v35, -v34, v34, 1.0
	v_rcp_f32_e32 v33, v33
	v_sqrt_f32_e32 v35, v35
	v_add_f32_e32 v32, 1.0, v32
	v_rcp_f32_e32 v32, v32
	v_lshlrev_b32_e32 v36, 16, v180
	v_mul_f32_e32 v33, v35, v33
	v_mul_f32_e32 v180, v33, v36
	v_mul_f32_e32 v32, v138, v32
	v_fmac_f32_e32 v180, v34, v179
	v_exp_f32_e32 v33, v58
	v_mul_f32_e32 v58, v34, v57
	v_exp_f32_e32 v32, v32
	v_exp_f32_e32 v34, v43
	v_add_f32_e32 v33, 1.0, v33
	v_rcp_f32_e32 v33, v33
	v_fma_f32 v35, -v32, v32, 1.0
	v_add_f32_e32 v34, 1.0, v34
	v_sqrt_f32_e32 v35, v35
	v_rcp_f32_e32 v34, v34
	s_waitcnt lgkmcnt(13)
	v_lshlrev_b32_e32 v36, 16, v181
	v_mul_f32_e32 v33, v35, v33
	v_mul_f32_e32 v34, v138, v34
	v_mul_f32_e32 v181, v33, v36
	v_exp_f32_e32 v33, v59
	v_exp_f32_e32 v34, v34
	v_fmac_f32_e32 v181, v32, v180
	v_mul_f32_e32 v59, v32, v58
	v_exp_f32_e32 v32, v44
	v_add_f32_e32 v33, 1.0, v33
	v_fma_f32 v35, -v34, v34, 1.0
	v_rcp_f32_e32 v33, v33
	v_sqrt_f32_e32 v35, v35
	v_add_f32_e32 v32, 1.0, v32
	v_rcp_f32_e32 v32, v32
	s_waitcnt lgkmcnt(12)
	v_lshlrev_b32_e32 v36, 16, v182
	v_mul_f32_e32 v33, v35, v33
	v_mul_f32_e32 v182, v33, v36
	v_mul_f32_e32 v32, v138, v32
	v_fmac_f32_e32 v182, v34, v181
	v_exp_f32_e32 v33, v60
	v_mul_f32_e32 v60, v34, v59
	v_exp_f32_e32 v32, v32
	v_exp_f32_e32 v34, v45
	v_add_f32_e32 v33, 1.0, v33
	v_rcp_f32_e32 v33, v33
	v_fma_f32 v35, -v32, v32, 1.0
	v_add_f32_e32 v34, 1.0, v34
	v_sqrt_f32_e32 v35, v35
	v_rcp_f32_e32 v34, v34
	s_waitcnt lgkmcnt(11)
	v_lshlrev_b32_e32 v36, 16, v183
	v_mul_f32_e32 v33, v35, v33
	v_mul_f32_e32 v34, v138, v34
	v_mul_f32_e32 v183, v33, v36
	v_exp_f32_e32 v33, v61
	v_exp_f32_e32 v34, v34
	v_fmac_f32_e32 v183, v32, v182
	v_mul_f32_e32 v61, v32, v60
	v_exp_f32_e32 v32, v46
	v_add_f32_e32 v33, 1.0, v33
	v_fma_f32 v35, -v34, v34, 1.0
	v_rcp_f32_e32 v33, v33
	v_sqrt_f32_e32 v35, v35
	v_add_f32_e32 v32, 1.0, v32
	v_rcp_f32_e32 v32, v32
	s_waitcnt lgkmcnt(10)
	v_lshlrev_b32_e32 v36, 16, v184
	v_mul_f32_e32 v33, v35, v33
	v_mul_f32_e32 v184, v33, v36
	v_fmac_f32_e32 v184, v34, v183
	v_exp_f32_e32 v33, v62
	v_mul_f32_e32 v62, v34, v61
	v_mul_f32_e32 v32, v138, v32
	v_exp_f32_e32 v34, v47
	v_exp_f32_e32 v32, v32
	v_add_f32_e32 v33, 1.0, v33
	v_rcp_f32_e32 v33, v33
	v_add_f32_e32 v34, 1.0, v34
	v_fma_f32 v35, -v32, v32, 1.0
	v_rcp_f32_e32 v34, v34
	v_sqrt_f32_e32 v35, v35
	s_waitcnt lgkmcnt(9)
	v_lshlrev_b32_e32 v36, 16, v185
	v_mul_f32_e32 v186, v32, v62
	v_mul_f32_e32 v34, v138, v34
	v_mul_f32_e32 v33, v35, v33
	v_exp_f32_e32 v35, v63
	v_exp_f32_e32 v34, v34
	v_mul_f32_e32 v63, v33, v36
	v_fmac_f32_e32 v63, v32, v184
	v_add_f32_e32 v33, 1.0, v35
	v_fma_f32 v35, -v34, v34, 1.0
	v_rcp_f32_e32 v33, v33
	v_sqrt_f32_e32 v35, v35
	s_waitcnt lgkmcnt(8)
	v_lshlrev_b32_e32 v32, 16, v187
	v_mul_f32_e32 v187, v34, v186
	v_mul_f32_e32 v33, v35, v33
	v_mul_f32_e32 v185, v33, v32
	v_fmac_f32_e32 v185, v34, v63
	v_mov_b32_e32 v188, v187
	v_mov_b32_e32 v252, v187
	v_mov_b32_e32 v189, v185
	v_mov_b32_e32 v253, v185
	s_nop 1
	v_permlane32_swap_b32 v188, v252
	v_permlane32_swap_b32 v189, v253
	s_and_saveexec_b64 s[18:19], vcc
	s_cbranch_execz .LBB0_299
	v_fma_f32 v32, v252, v189, v253
	v_mul_f32_e32 v33, v188, v252
	v_add_u32_e32 v35, s98, v147
	ds_write2_b32 v35, v33, v32 offset1:32
; #define LAS __attribute__((address_space(3)))
; __device__ __forceinline__ unsigned cvt_pk_bf16(float lo, float hi) { unsigned r; asm volatile("v_cvt_pk_bf16_f32 %0, %1, %2" : "=v"(r) : "v"(lo), "v"(hi)); return r; }
; __device__ __forceinline__ float bf_lo(unsigned u) { return __uint_as_float(u << 16); }
; __device__ __forceinline__ float bf_hi(unsigned u) { return __uint_as_float(u & 0xffff0000u); }
; __device__ __forceinline__ bf16_t f2bf(float f) { return (bf16_t)(cvt_pk_bf16(f, 0.f) & 0xffffu); }
; #define LDS_BARRIER() do { asm volatile("s_waitcnt lgkmcnt(0)" ::: "memory"); __builtin_amdgcn_s_barrier(); asm volatile("" ::: "memory"); } while (0)
; template <int dir>
; __device__ __forceinline__ void lru_pass(LAS unsigned char* lds, const Params& P, int b, int h, int q, bool dry) {
;     ...
;             LDS_BARRIER();
;             float cin = carry, cend = carry;
; #pragma unroll
;             for (int w = 0; w < 8; ++w) { const float pw = AGG[(w * 2 + 0) * 32 + nl], ew = AGG[(w * 2 + 1) * 32 + nl]; if (w == wid) cin = cend; cend = fmaf(pw, cend, ew); }
;             carry = cend;
;             if (g) cin = fmaf(P0, cin, E0);
;             if (!isctx) {
; #pragma unroll
;                 for (int v = 0; v < 16; ++v) { const float hv = fmaf(zi[v], cin, zr[v]);
;                     const int s = sbase + v; const int tl = dir == 0 ? s : 255 - s;
;                     if (dir == 0) *(LAS unsigned*)(TOUT + tl * IO_WP + nl * 4) = (cvt_pk_bf16(hv, 0.f) & 0xffffu) | (pk[v] << 16);
;                     else *(LAS bf16_t*)(TOUT + tl * IO_NP + nl * 2) = f2bf((bf_lo(pk[v]) + hv) * bf_hi(pk[v])); }
.LBB0_299:
	s_or_b64 exec, exec, s[18:19]
	s_waitcnt lgkmcnt(0)
	s_barrier
	s_setprio 1
	v_add_u32_e32 v34, s99, v140
	ds_read2_b32 v[36:37], v34 offset1:32
	ds_read2_b32 v[38:39], v34 offset0:64 offset1:96
	ds_read2_b32 v[40:41], v34 offset0:128 offset1:160
	ds_read2_b32 v[42:43], v34 offset0:192 offset1:224
	v_add_u32_e32 v32, s100, v140
	ds_read2_b32 v[44:45], v32 offset1:32
	s_waitcnt lgkmcnt(4)
	v_fmac_f32_e32 v37, v36, v165
	ds_read2_b32 v[46:47], v32 offset0:64 offset1:96
	s_waitcnt lgkmcnt(4)
	v_fmac_f32_e32 v39, v38, v37
	ds_read2_b32 v[34:35], v32 offset0:128 offset1:160
	s_waitcnt lgkmcnt(4)
	v_fmac_f32_e32 v41, v40, v39
	ds_read2_b32 v[32:33], v32 offset0:192 offset1:224
	s_waitcnt lgkmcnt(4)
	v_fmac_f32_e32 v43, v42, v41
	s_waitcnt lgkmcnt(3)
	v_fmac_f32_e32 v45, v44, v43
	s_waitcnt lgkmcnt(2)
	v_fmac_f32_e32 v47, v46, v45
	s_cmp_eq_u32 s80, 0
	s_waitcnt lgkmcnt(1)
	v_fmac_f32_e32 v35, v34, v47
	s_cbranch_scc1 .LBB0_301
	v_cndmask_b32_e64 v37, v165, v37, s[14:15]
	v_cndmask_b32_e64 v37, v37, v39, s[12:13]
	v_cndmask_b32_e64 v37, v37, v41, s[10:11]
	v_cndmask_b32_e64 v37, v37, v43, s[8:9]
	v_cndmask_b32_e64 v37, v37, v45, s[4:5]
	v_cndmask_b32_e64 v37, v37, v47, s[16:17]
	v_cndmask_b32_e64 v37, v37, v35, s[0:1]
	v_fmac_f32_e32 v189, v188, v37
	v_cndmask_b32_e32 v34, v189, v37, vcc
	v_fmac_f32_e32 v49, v171, v34
	v_fmac_f32_e32 v172, v50, v34
	v_fmac_f32_e32 v173, v51, v34
	v_fmac_f32_e32 v174, v52, v34
	v_fmac_f32_e32 v175, v53, v34
	v_fmac_f32_e32 v176, v54, v34
	v_fmac_f32_e32 v177, v55, v34
	v_fmac_f32_e32 v178, v56, v34
	v_fmac_f32_e32 v179, v57, v34
	v_fmac_f32_e32 v180, v58, v34
	v_fmac_f32_e32 v181, v59, v34
	v_fmac_f32_e32 v182, v60, v34
	v_fmac_f32_e32 v183, v61, v34
	v_fmac_f32_e32 v184, v62, v34
	v_fmac_f32_e32 v63, v186, v34
	v_fmac_f32_e32 v185, v187, v34
	v_lshlrev_b32_e32 v37, 16, v127
	v_cvt_pk_bf16_f32 v36, v49, v37
	ds_write_b32 v164, v36
	v_lshlrev_b32_e32 v39, 16, v124
	v_cvt_pk_bf16_f32 v38, v172, v39
	ds_write_b32 v164, v38 offset:144
	v_lshlrev_b32_e32 v41, 16, v121
	v_cvt_pk_bf16_f32 v40, v173, v41
	ds_write_b32 v164, v40 offset:288
	v_lshlrev_b32_e32 v43, 16, v66
	v_cvt_pk_bf16_f32 v42, v174, v43
	ds_write_b32 v164, v42 offset:432
	v_lshlrev_b32_e32 v37, 16, v64
	v_cvt_pk_bf16_f32 v36, v175, v37
	ds_write_b32 v164, v36 offset:576
	v_lshlrev_b32_e32 v39, 16, v126
	v_cvt_pk_bf16_f32 v38, v176, v39
	ds_write_b32 v164, v38 offset:720
	v_lshlrev_b32_e32 v41, 16, v123
	v_cvt_pk_bf16_f32 v40, v177, v41
	ds_write_b32 v164, v40 offset:864
	v_lshlrev_b32_e32 v43, 16, v120
	v_cvt_pk_bf16_f32 v42, v178, v43
	ds_write_b32 v164, v42 offset:1008
	v_lshlrev_b32_e32 v37, 16, v170
	v_cvt_pk_bf16_f32 v36, v179, v37
	ds_write_b32 v164, v36 offset:1152
	v_lshlrev_b32_e32 v39, 16, v169
	v_cvt_pk_bf16_f32 v38, v180, v39
	ds_write_b32 v164, v38 offset:1296
	v_lshlrev_b32_e32 v41, 16, v168
	v_cvt_pk_bf16_f32 v40, v181, v41
	ds_write_b32 v164, v40 offset:1440
	v_lshlrev_b32_e32 v43, 16, v166
	v_cvt_pk_bf16_f32 v42, v182, v43
	ds_write_b32 v164, v42 offset:1584
	v_lshlrev_b32_e32 v37, 16, v125
	v_cvt_pk_bf16_f32 v36, v183, v37
	ds_write_b32 v164, v36 offset:1728
	v_lshlrev_b32_e32 v39, 16, v122
	v_cvt_pk_bf16_f32 v38, v184, v39
	ds_write_b32 v164, v38 offset:1872
	v_lshlrev_b32_e32 v41, 16, v67
	v_cvt_pk_bf16_f32 v40, v63, v41
	ds_write_b32 v164, v40 offset:2016
	v_lshlrev_b32_e32 v43, 16, v48
	v_cvt_pk_bf16_f32 v42, v185, v43
	ds_write_b32 v164, v42 offset:2160

; #define LAS __attribute__((address_space(3)))
; template <int dir>
; __device__ __forceinline__ void lru_pass(LAS unsigned char* lds, const Params& P, int b, int h, int q, bool dry) {
;     ...
;             { const int sl = 32 * wid + s_i; const int tlA = dir == 0 ? sl : 255 - sl;
;               const LAS unsigned char* ap = XC + tlA * XC_PITCH + 16 * g;
;               const LAS unsigned char* wrp = WB + nl * XC_PITCH + 16 * g; const LAS unsigned char* wip = wrp + 32 * XC_PITCH;
; #pragma unroll
;               for (int ks = 0; ks < 8; ++ks) { const bf16x8 A = *(const LAS bf16x8*)(ap + 32 * ks);
;                   const bf16x8 Br = *(const LAS bf16x8*)(wrp + 32 * ks), Bi = *(const LAS bf16x8*)(wip + 32 * ks);
;                   zr = __builtin_amdgcn_mfma_f32_32x32x16_bf16(A, Br, zr, 0, 0, 0); zi = __builtin_amdgcn_mfma_f32_32x32x16_bf16(A, Bi, zi, 0, 0, 0); } }
;             unsigned xcb[16], pk[16];
; #pragma unroll
;             for (int v = 0; v < 16; ++v) { const int s = sbase + v; const int tl = dir == 0 ? s : 255 - s; xcb[v] = *(const LAS bf16_t*)(XC + tl * XC_PITCH + chl * 2);
;                 if (dir == 0) pk[v] = *(const LAS bf16_t*)(TIN + tl * IO_NP + nl * 2); else pk[v] = *(const LAS unsigned*)(TIN + tl * IO_WP + nl * 4); }
;             float Pp = 1.f, E = 0.f;
; #pragma unroll
;             for (int v = 0; v < 16; ++v) {
;                 const float xcv = __uint_as_float(xcb[v] << 16);
;                 const float r = __builtin_amdgcn_rcpf(1.0f + __builtin_amdgcn_exp2f(zr[v]));
;                 const float ig = __builtin_amdgcn_rcpf(1.0f + __builtin_amdgcn_exp2f(zi[v]));
;                 const float a = __builtin_amdgcn_exp2f(cl * r);
;                 const float sq = __builtin_amdgcn_sqrtf(fmaf(-a, a, 1.0f));
;                 const float u = sq * ig * xcv;
;                 E = fmaf(a, E, u); Pp *= a; zr[v] = E; zi[v] = Pp; }
.LBB0_311:
	ds_read_b128 v[128:131], v172
	ds_read_b128 v[48:51], v173
	ds_read_b128 v[132:135], v172 offset:32
	ds_read_b128 v[52:55], v173 offset:32
	s_waitcnt lgkmcnt(2)
	v_mfma_f32_32x32x16_bf16 v[32:47], v[128:131], v[48:51], v[0:15]
	s_waitcnt lgkmcnt(0)
	v_mfma_f32_32x32x16_bf16 v[32:47], v[132:135], v[52:55], v[32:47]
	ds_read_b128 v[224:227], v172 offset:64
	ds_read_b128 v[48:51], v173 offset:64
	ds_read_b128 v[228:231], v172 offset:96
	ds_read_b128 v[52:55], v173 offset:96
	s_waitcnt lgkmcnt(2)
	v_mfma_f32_32x32x16_bf16 v[32:47], v[224:227], v[48:51], v[32:47]
	s_waitcnt lgkmcnt(0)
	v_mfma_f32_32x32x16_bf16 v[32:47], v[228:231], v[52:55], v[32:47]
	ds_read_b128 v[232:235], v172 offset:128
	ds_read_b128 v[48:51], v173 offset:128
	ds_read_b128 v[236:239], v172 offset:160
	ds_read_b128 v[52:55], v173 offset:160
	s_waitcnt lgkmcnt(2)
	v_mfma_f32_32x32x16_bf16 v[32:47], v[232:235], v[48:51], v[32:47]
	s_waitcnt lgkmcnt(0)
	v_mfma_f32_32x32x16_bf16 v[32:47], v[236:239], v[52:55], v[32:47]
	ds_read_b128 v[240:243], v172 offset:192
	ds_read_b128 v[48:51], v173 offset:192
	ds_read_b128 v[244:247], v172 offset:224
	ds_read_b128 v[52:55], v173 offset:224
	ds_read_b128 v[248:251], v173 offset:8704
	ds_read_b128 v[146:149], v173 offset:8736
	s_waitcnt lgkmcnt(4)
	v_mfma_f32_32x32x16_bf16 v[32:47], v[240:243], v[48:51], v[32:47]
	s_waitcnt lgkmcnt(2)
	v_mfma_f32_32x32x16_bf16 v[32:47], v[244:247], v[52:55], v[32:47]
	s_waitcnt lgkmcnt(1)
	v_mfma_f32_32x32x16_bf16 v[48:63], v[128:131], v[248:251], v[16:31]
	s_nop 9
	v_exp_f32_e32 v32, v32
	v_exp_f32_e32 v33, v33
	v_exp_f32_e32 v34, v34
	v_add_f32_e32 v32, 1.0, v32
	v_rcp_f32_e32 v32, v32
	v_add_f32_e32 v33, 1.0, v33
	s_waitcnt lgkmcnt(0)
	v_mfma_f32_32x32x16_bf16 v[48:63], v[132:135], v[146:149], v[48:63]
	ds_read_b128 v[128:131], v173 offset:8768
	ds_read_b128 v[132:135], v173 offset:8800
	v_mul_f32_e32 v32, v159, v32
	v_rcp_f32_e32 v33, v33
	s_nop 0
	v_mul_f32_e32 v33, v159, v33
	s_waitcnt lgkmcnt(1)
	v_mfma_f32_32x32x16_bf16 v[48:63], v[224:227], v[128:131], v[48:63]
	v_exp_f32_e32 v227, v32
	v_exp_f32_e32 v33, v33
	s_waitcnt lgkmcnt(0)
	v_mfma_f32_32x32x16_bf16 v[48:63], v[228:231], v[132:135], v[48:63]
	ds_read_b128 v[128:131], v173 offset:8832
	ds_read_b128 v[132:135], v173 offset:8864
	ds_read_b128 v[146:149], v173 offset:8896
	ds_read_b128 v[228:231], v173 offset:8928
	s_waitcnt lgkmcnt(3)
	v_mfma_f32_32x32x16_bf16 v[48:63], v[232:235], v[128:131], v[48:63]
	ds_read_u16 v162, v174
	ds_read_b32 v226, v175
	ds_read_u16 v163, v176
	ds_read_b32 v225, v177
	ds_read_u16 v232, v178
	ds_read_b32 v224, v179
	ds_read_u16 v233, v180
	ds_read_b32 v223, v181
	s_waitcnt lgkmcnt(7)
	v_lshlrev_b32_e32 v162, 16, v162
	s_waitcnt lgkmcnt(5)
	v_lshlrev_b32_e32 v163, 16, v163
	v_mfma_f32_32x32x16_bf16 v[48:63], v[236:239], v[132:135], v[48:63]
	ds_read_u16 v234, v182
	ds_read_b32 v135, v183
	ds_read_u16 v235, v184
	ds_read_b32 v134, v185
	ds_read_u16 v236, v186
	ds_read_b32 v133, v187
	ds_read_u16 v237, v188
	ds_read_b32 v131, v189
	v_mfma_f32_32x32x16_bf16 v[48:63], v[240:243], v[146:149], v[48:63]
	ds_read_u16 v146, v190
	ds_read_b32 v132, v191
	ds_read_u16 v147, v192
	ds_read_b32 v130, v193
	ds_read_u16 v148, v194
	ds_read_b32 v129, v195
	ds_read_u16 v149, v196
	ds_read_b32 v128, v197
	v_mfma_f32_32x32x16_bf16 v[48:63], v[244:247], v[228:231], v[48:63]
	s_nop 11
	v_exp_f32_e32 v228, v48
	ds_read_u16 v239, v198
	ds_read_b32 v67, v199
	ds_read_u16 v240, v200
	ds_read_b32 v66, v201
	ds_read_u16 v241, v202
	ds_read_b32 v64, v203
	ds_read_u16 v242, v204
	ds_read_b32 v48, v205
	v_add_f32_e32 v32, 1.0, v228
	v_fma_f32 v228, -v227, v227, 1.0
	v_rcp_f32_e32 v32, v32
	v_sqrt_f32_e32 v228, v228
	s_nop 0
	v_mul_f32_e32 v32, v228, v32
	v_exp_f32_e32 v228, v49
	v_mul_f32_e32 v49, v32, v162
	v_fma_f32 v162, -v33, v33, 1.0
	v_sqrt_f32_e32 v162, v162
	v_add_f32_e32 v32, 1.0, v228
	v_rcp_f32_e32 v32, v32
	v_fmac_f32_e32 v49, 0, v227
	v_mul_f32_e32 v32, v162, v32
	v_mul_f32_e32 v228, v32, v163
	v_add_f32_e32 v32, 1.0, v34
	v_rcp_f32_e32 v32, v32
	v_exp_f32_e32 v34, v50
	v_fmac_f32_e32 v228, v33, v49
	v_mul_f32_e32 v50, v227, v33
	v_mul_f32_e32 v32, v159, v32
	v_exp_f32_e32 v32, v32
	v_add_f32_e32 v33, 1.0, v34
	v_exp_f32_e32 v34, v35
	v_rcp_f32_e32 v33, v33
	v_fma_f32 v35, -v32, v32, 1.0
	v_sqrt_f32_e32 v35, v35
	v_add_f32_e32 v34, 1.0, v34
	v_rcp_f32_e32 v34, v34
	s_waitcnt lgkmcnt(14)
; template <int dir>
; __device__ __forceinline__ void lru_pass(LAS unsigned char* lds, const Params& P, int b, int h, int q, bool dry) {
;     ...
;             for (int v = 0; v < 16; ++v) {
;                 const float xcv = __uint_as_float(xcb[v] << 16);
;                 const float r = __builtin_amdgcn_rcpf(1.0f + __builtin_amdgcn_exp2f(zr[v]));
;                 const float ig = __builtin_amdgcn_rcpf(1.0f + __builtin_amdgcn_exp2f(zi[v]));
;                 const float a = __builtin_amdgcn_exp2f(cl * r);
;                 const float sq = __builtin_amdgcn_sqrtf(fmaf(-a, a, 1.0f));
;                 const float u = sq * ig * xcv;
;                 E = fmaf(a, E, u); Pp *= a; zr[v] = E; zi[v] = Pp; }
;             const float Po = __shfl_xor(Pp, 32), Eo = __shfl_xor(E, 32);
;             const float P0 = g ? Po : Pp, E0 = g ? Eo : E, P1 = g ? Pp : Po, E1 = g ? E : Eo;
;             if (g == 0) { AGG[(wid * 2 + 0) * 32 + nl] = P0 * P1; AGG[(wid * 2 + 1) * 32 + nl] = fmaf(P1, E0, E1); }
	v_lshlrev_b32_e32 v162, 16, v232
	v_mul_f32_e32 v33, v35, v33
	v_mul_f32_e32 v229, v33, v162
	v_mul_f32_e32 v34, v159, v34
	v_exp_f32_e32 v33, v51
	v_exp_f32_e32 v34, v34
	v_fmac_f32_e32 v229, v32, v228
	v_mul_f32_e32 v51, v32, v50
	v_exp_f32_e32 v32, v36
	v_add_f32_e32 v33, 1.0, v33
	v_fma_f32 v35, -v34, v34, 1.0
	v_rcp_f32_e32 v33, v33
	v_sqrt_f32_e32 v35, v35
	v_add_f32_e32 v32, 1.0, v32
	v_rcp_f32_e32 v32, v32
	v_lshlrev_b32_e32 v36, 16, v233
	v_mul_f32_e32 v33, v35, v33
	v_mul_f32_e32 v230, v33, v36
	v_mul_f32_e32 v32, v159, v32
	v_fmac_f32_e32 v230, v34, v229
	v_exp_f32_e32 v33, v52
	v_mul_f32_e32 v52, v34, v51
	v_exp_f32_e32 v32, v32
	v_exp_f32_e32 v34, v37
	v_add_f32_e32 v33, 1.0, v33
	v_rcp_f32_e32 v33, v33
	v_fma_f32 v35, -v32, v32, 1.0
	v_add_f32_e32 v34, 1.0, v34
	v_sqrt_f32_e32 v35, v35
	v_rcp_f32_e32 v34, v34
	v_lshlrev_b32_e32 v36, 16, v234
	v_mul_f32_e32 v33, v35, v33
	v_mul_f32_e32 v34, v159, v34
	v_mul_f32_e32 v231, v33, v36
	v_exp_f32_e32 v33, v53
	v_exp_f32_e32 v34, v34
	v_fmac_f32_e32 v231, v32, v230
	v_mul_f32_e32 v53, v32, v52
	v_exp_f32_e32 v32, v38
	v_add_f32_e32 v33, 1.0, v33
	v_fma_f32 v35, -v34, v34, 1.0
	v_rcp_f32_e32 v33, v33
	v_sqrt_f32_e32 v35, v35
	v_add_f32_e32 v32, 1.0, v32
	v_rcp_f32_e32 v32, v32
	v_lshlrev_b32_e32 v36, 16, v235
	v_mul_f32_e32 v33, v35, v33
	v_mul_f32_e32 v232, v33, v36
	v_mul_f32_e32 v32, v159, v32
	v_fmac_f32_e32 v232, v34, v231
	v_exp_f32_e32 v33, v54
	v_mul_f32_e32 v54, v34, v53
	v_exp_f32_e32 v32, v32
	v_exp_f32_e32 v34, v39
	v_add_f32_e32 v33, 1.0, v33
	v_rcp_f32_e32 v33, v33
	v_fma_f32 v35, -v32, v32, 1.0
	v_add_f32_e32 v34, 1.0, v34
	v_sqrt_f32_e32 v35, v35
	v_rcp_f32_e32 v34, v34
	v_lshlrev_b32_e32 v36, 16, v236
	v_mul_f32_e32 v33, v35, v33
	v_mul_f32_e32 v34, v159, v34
	v_mul_f32_e32 v233, v33, v36
	v_exp_f32_e32 v33, v55
	v_exp_f32_e32 v34, v34
	v_fmac_f32_e32 v233, v32, v232
	v_mul_f32_e32 v55, v32, v54
	v_exp_f32_e32 v32, v40
	v_add_f32_e32 v33, 1.0, v33
	v_fma_f32 v35, -v34, v34, 1.0
	v_rcp_f32_e32 v33, v33
	v_sqrt_f32_e32 v35, v35
	v_add_f32_e32 v32, 1.0, v32
	v_rcp_f32_e32 v32, v32
	v_lshlrev_b32_e32 v36, 16, v237
	v_mul_f32_e32 v33, v35, v33
	v_mul_f32_e32 v234, v33, v36
	v_mul_f32_e32 v32, v159, v32
	v_fmac_f32_e32 v234, v34, v233
	v_exp_f32_e32 v33, v56
	v_mul_f32_e32 v56, v34, v55
	v_exp_f32_e32 v32, v32
	v_exp_f32_e32 v34, v41
	v_add_f32_e32 v33, 1.0, v33
	v_rcp_f32_e32 v33, v33
	v_fma_f32 v35, -v32, v32, 1.0
	v_add_f32_e32 v34, 1.0, v34
	v_sqrt_f32_e32 v35, v35
	v_rcp_f32_e32 v34, v34
	v_lshlrev_b32_e32 v36, 16, v146
	v_mul_f32_e32 v33, v35, v33
	v_mul_f32_e32 v34, v159, v34
	v_mul_f32_e32 v235, v33, v36
	v_exp_f32_e32 v33, v57
	v_exp_f32_e32 v34, v34
	v_fmac_f32_e32 v235, v32, v234
	v_mul_f32_e32 v57, v32, v56
	v_exp_f32_e32 v32, v42
	v_add_f32_e32 v33, 1.0, v33
	v_fma_f32 v35, -v34, v34, 1.0
	v_rcp_f32_e32 v33, v33
	v_sqrt_f32_e32 v35, v35
	v_add_f32_e32 v32, 1.0, v32
	v_rcp_f32_e32 v32, v32
	s_waitcnt lgkmcnt(13)
	v_lshlrev_b32_e32 v36, 16, v147
	v_mul_f32_e32 v33, v35, v33
	v_mul_f32_e32 v236, v33, v36
	v_mul_f32_e32 v32, v159, v32
	v_fmac_f32_e32 v236, v34, v235
	v_exp_f32_e32 v33, v58
	v_mul_f32_e32 v58, v34, v57
	v_exp_f32_e32 v32, v32
	v_exp_f32_e32 v34, v43
	v_add_f32_e32 v33, 1.0, v33
	v_rcp_f32_e32 v33, v33
	v_fma_f32 v35, -v32, v32, 1.0
	v_add_f32_e32 v34, 1.0, v34
	v_sqrt_f32_e32 v35, v35
	v_rcp_f32_e32 v34, v34
	s_waitcnt lgkmcnt(11)
	v_lshlrev_b32_e32 v36, 16, v148
	v_mul_f32_e32 v33, v35, v33
	v_mul_f32_e32 v34, v159, v34
	v_mul_f32_e32 v237, v33, v36
	v_exp_f32_e32 v33, v59
	v_exp_f32_e32 v34, v34
	v_fmac_f32_e32 v237, v32, v236
	v_mul_f32_e32 v59, v32, v58
	v_exp_f32_e32 v32, v44
	v_add_f32_e32 v33, 1.0, v33
	v_fma_f32 v35, -v34, v34, 1.0
	v_rcp_f32_e32 v33, v33
	v_sqrt_f32_e32 v35, v35
	v_add_f32_e32 v32, 1.0, v32
	v_rcp_f32_e32 v32, v32
	s_waitcnt lgkmcnt(9)
	v_lshlrev_b32_e32 v36, 16, v149
	v_mul_f32_e32 v33, v35, v33
	v_mul_f32_e32 v238, v33, v36
	v_mul_f32_e32 v32, v159, v32
	v_fmac_f32_e32 v238, v34, v237
	v_exp_f32_e32 v33, v60
	v_mul_f32_e32 v60, v34, v59
	v_exp_f32_e32 v32, v32
	v_exp_f32_e32 v34, v45
	v_add_f32_e32 v33, 1.0, v33
	v_rcp_f32_e32 v33, v33
	v_fma_f32 v35, -v32, v32, 1.0
	v_add_f32_e32 v34, 1.0, v34
	v_sqrt_f32_e32 v35, v35
	v_rcp_f32_e32 v34, v34
	s_waitcnt lgkmcnt(7)
	v_lshlrev_b32_e32 v36, 16, v239
	v_mul_f32_e32 v33, v35, v33
	v_mul_f32_e32 v34, v159, v34
	v_mul_f32_e32 v239, v33, v36
	v_exp_f32_e32 v33, v61
	v_exp_f32_e32 v34, v34
	v_fmac_f32_e32 v239, v32, v238
	v_mul_f32_e32 v61, v32, v60
	v_exp_f32_e32 v32, v46
	v_add_f32_e32 v33, 1.0, v33
	v_fma_f32 v35, -v34, v34, 1.0
	v_rcp_f32_e32 v33, v33
	v_sqrt_f32_e32 v35, v35
	v_add_f32_e32 v32, 1.0, v32
	v_rcp_f32_e32 v32, v32
	s_waitcnt lgkmcnt(5)
	v_lshlrev_b32_e32 v36, 16, v240
	v_mul_f32_e32 v33, v35, v33
	v_mul_f32_e32 v240, v33, v36
	v_fmac_f32_e32 v240, v34, v239
	v_exp_f32_e32 v33, v62
	v_mul_f32_e32 v62, v34, v61
	v_mul_f32_e32 v32, v159, v32
	v_exp_f32_e32 v34, v47
	v_exp_f32_e32 v32, v32
	v_add_f32_e32 v33, 1.0, v33
	v_rcp_f32_e32 v33, v33
	v_add_f32_e32 v34, 1.0, v34
	v_fma_f32 v35, -v32, v32, 1.0
	v_rcp_f32_e32 v34, v34
	v_sqrt_f32_e32 v35, v35
	s_waitcnt lgkmcnt(3)
	v_lshlrev_b32_e32 v36, 16, v241
	v_mul_f32_e32 v243, v32, v62
	v_mul_f32_e32 v34, v159, v34
	v_mul_f32_e32 v33, v35, v33
	v_exp_f32_e32 v35, v63
	v_exp_f32_e32 v34, v34
	v_mul_f32_e32 v63, v33, v36
	v_fmac_f32_e32 v63, v32, v240
	v_add_f32_e32 v33, 1.0, v35
	v_fma_f32 v35, -v34, v34, 1.0
	v_rcp_f32_e32 v33, v33
	v_sqrt_f32_e32 v35, v35
	s_waitcnt lgkmcnt(1)
	v_lshlrev_b32_e32 v32, 16, v242
	v_mul_f32_e32 v242, v34, v243
	v_mul_f32_e32 v33, v35, v33
	v_mul_f32_e32 v241, v33, v32
	v_fmac_f32_e32 v241, v34, v63
	v_mov_b32_e32 v244, v242
	v_mov_b32_e32 v246, v242
	v_mov_b32_e32 v245, v241
	v_mov_b32_e32 v247, v241
	s_nop 1
	v_permlane32_swap_b32 v244, v246
	v_permlane32_swap_b32 v245, v247
	s_and_saveexec_b64 s[18:19], vcc
	s_cbranch_execz .LBB0_313
	v_fma_f32 v32, v246, v245, v247
	v_mul_f32_e32 v33, v244, v246
	v_add_u32_e32 v35, s98, v254
	ds_write2_b32 v35, v33, v32 offset1:32
; #define LAS __attribute__((address_space(3)))
; __device__ __forceinline__ unsigned cvt_pk_bf16(float lo, float hi) { unsigned r; asm volatile("v_cvt_pk_bf16_f32 %0, %1, %2" : "=v"(r) : "v"(lo), "v"(hi)); return r; }
; __device__ __forceinline__ float bf_lo(unsigned u) { return __uint_as_float(u << 16); }
; __device__ __forceinline__ float bf_hi(unsigned u) { return __uint_as_float(u & 0xffff0000u); }
; __device__ __forceinline__ bf16_t f2bf(float f) { return (bf16_t)(cvt_pk_bf16(f, 0.f) & 0xffffu); }
; #define LDS_BARRIER() do { asm volatile("s_waitcnt lgkmcnt(0)" ::: "memory"); __builtin_amdgcn_s_barrier(); asm volatile("" ::: "memory"); } while (0)
; template <int dir>
; __device__ __forceinline__ void lru_pass(LAS unsigned char* lds, const Params& P, int b, int h, int q, bool dry) {
;     ...
;             LDS_BARRIER();
;             float cin = carry, cend = carry;
; #pragma unroll
;             for (int w = 0; w < 8; ++w) { const float pw = AGG[(w * 2 + 0) * 32 + nl], ew = AGG[(w * 2 + 1) * 32 + nl]; if (w == wid) cin = cend; cend = fmaf(pw, cend, ew); }
;             carry = cend;
;             if (g) cin = fmaf(P0, cin, E0);
;             if (!isctx) {
; #pragma unroll
;                 for (int v = 0; v < 16; ++v) { const float hv = fmaf(zi[v], cin, zr[v]);
;                     const int s = sbase + v; const int tl = dir == 0 ? s : 255 - s;
;                     if (dir == 0) *(LAS unsigned*)(TOUT + tl * IO_WP + nl * 4) = (cvt_pk_bf16(hv, 0.f) & 0xffffu) | (pk[v] << 16);
;                     else *(LAS bf16_t*)(TOUT + tl * IO_NP + nl * 2) = f2bf((bf_lo(pk[v]) + hv) * bf_hi(pk[v])); }
.LBB0_313:
	s_or_b64 exec, exec, s[18:19]
	s_waitcnt lgkmcnt(0)
	s_barrier
	s_setprio 1
	v_add_u32_e32 v34, s99, v161
	ds_read2_b32 v[36:37], v34 offset1:32
	ds_read2_b32 v[38:39], v34 offset0:64 offset1:96
	ds_read2_b32 v[40:41], v34 offset0:128 offset1:160
	ds_read2_b32 v[42:43], v34 offset0:192 offset1:224
	v_add_u32_e32 v32, s100, v161
	s_waitcnt lgkmcnt(3)
	v_fmac_f32_e32 v37, v36, v222
	s_waitcnt lgkmcnt(2)
	v_fmac_f32_e32 v39, v38, v37
	s_waitcnt lgkmcnt(1)
	v_fmac_f32_e32 v41, v40, v39
	ds_read2_b32 v[44:45], v32 offset1:32
	ds_read2_b32 v[46:47], v32 offset0:64 offset1:96
	ds_read2_b32 v[34:35], v32 offset0:128 offset1:160
	ds_read2_b32 v[32:33], v32 offset0:192 offset1:224
	s_waitcnt lgkmcnt(4)
	v_fmac_f32_e32 v43, v42, v41
	s_waitcnt lgkmcnt(3)
	v_fmac_f32_e32 v45, v44, v43
	s_waitcnt lgkmcnt(2)
	v_fmac_f32_e32 v47, v46, v45
	s_cmp_eq_u32 s44, 0
	s_waitcnt lgkmcnt(1)
	v_fmac_f32_e32 v35, v34, v47
	s_cbranch_scc1 .LBB0_315
	v_cndmask_b32_e64 v37, v222, v37, s[14:15]
	v_cndmask_b32_e64 v37, v37, v39, s[12:13]
	v_cndmask_b32_e64 v37, v37, v41, s[10:11]
	v_cndmask_b32_e64 v37, v37, v43, s[8:9]
	v_cndmask_b32_e64 v37, v37, v45, s[4:5]
	v_cndmask_b32_e64 v37, v37, v47, s[16:17]
	v_cndmask_b32_e64 v37, v37, v35, s[0:1]
	v_fmac_f32_e32 v245, v244, v37
	v_cndmask_b32_e32 v34, v245, v37, vcc
	v_fmac_f32_e32 v49, v227, v34
	v_fmac_f32_e32 v228, v50, v34
	v_fmac_f32_e32 v229, v51, v34
	v_fmac_f32_e32 v230, v52, v34
	v_fmac_f32_e32 v231, v53, v34
	v_fmac_f32_e32 v232, v54, v34
	v_fmac_f32_e32 v233, v55, v34
	v_fmac_f32_e32 v234, v56, v34
	v_fmac_f32_e32 v235, v57, v34
	v_fmac_f32_e32 v236, v58, v34
	v_fmac_f32_e32 v237, v59, v34
	v_fmac_f32_e32 v238, v60, v34
	v_fmac_f32_e32 v239, v61, v34
	v_fmac_f32_e32 v240, v62, v34
	v_fmac_f32_e32 v63, v243, v34
	v_fmac_f32_e32 v241, v242, v34
	v_lshlrev_b32_e32 v36, 16, v226
	v_lshlrev_b32_e32 v38, 16, v225
	v_add_f32_e32 v36, v49, v36
	v_add_f32_e32 v38, v228, v38
	v_and_b32_e32 v37, 0xffff0000, v226
	v_and_b32_e32 v39, 0xffff0000, v225
	v_mul_f32_e32 v36, v36, v37
	v_mul_f32_e32 v38, v38, v39
	v_cvt_pk_bf16_f32 v36, v36, v38
	ds_write_b16 v206, v36
	ds_write_b16_d16_hi v207, v36
	v_lshlrev_b32_e32 v40, 16, v224
	v_lshlrev_b32_e32 v42, 16, v223
	v_add_f32_e32 v40, v229, v40
	v_add_f32_e32 v42, v230, v42
	v_and_b32_e32 v41, 0xffff0000, v224
	v_and_b32_e32 v43, 0xffff0000, v223
	v_mul_f32_e32 v40, v40, v41
	v_mul_f32_e32 v42, v42, v43
	v_cvt_pk_bf16_f32 v40, v40, v42
	ds_write_b16 v208, v40
	ds_write_b16_d16_hi v209, v40
	v_lshlrev_b32_e32 v36, 16, v135
	v_lshlrev_b32_e32 v38, 16, v134
	v_add_f32_e32 v36, v231, v36
	v_add_f32_e32 v38, v232, v38
	v_and_b32_e32 v37, 0xffff0000, v135
	v_and_b32_e32 v39, 0xffff0000, v134
	v_mul_f32_e32 v36, v36, v37
	v_mul_f32_e32 v38, v38, v39
	v_cvt_pk_bf16_f32 v36, v36, v38
	ds_write_b16 v210, v36
	ds_write_b16_d16_hi v211, v36
	v_lshlrev_b32_e32 v40, 16, v133
	v_lshlrev_b32_e32 v42, 16, v131
	v_add_f32_e32 v40, v233, v40
	v_add_f32_e32 v42, v234, v42
	v_and_b32_e32 v41, 0xffff0000, v133
	v_and_b32_e32 v43, 0xffff0000, v131
	v_mul_f32_e32 v40, v40, v41
	v_mul_f32_e32 v42, v42, v43
	v_cvt_pk_bf16_f32 v40, v40, v42
	ds_write_b16 v212, v40
	ds_write_b16_d16_hi v213, v40
	v_lshlrev_b32_e32 v36, 16, v132
	v_lshlrev_b32_e32 v38, 16, v130
	v_add_f32_e32 v36, v235, v36
	v_add_f32_e32 v38, v236, v38
	v_and_b32_e32 v37, 0xffff0000, v132
	v_and_b32_e32 v39, 0xffff0000, v130
	v_mul_f32_e32 v36, v36, v37
	v_mul_f32_e32 v38, v38, v39
	v_cvt_pk_bf16_f32 v36, v36, v38
	ds_write_b16 v214, v36
	ds_write_b16_d16_hi v215, v36
	v_lshlrev_b32_e32 v40, 16, v129
	v_lshlrev_b32_e32 v42, 16, v128
	v_add_f32_e32 v40, v237, v40
	v_add_f32_e32 v42, v238, v42
	v_and_b32_e32 v41, 0xffff0000, v129
	v_and_b32_e32 v43, 0xffff0000, v128
	v_mul_f32_e32 v40, v40, v41
	v_mul_f32_e32 v42, v42, v43
	v_cvt_pk_bf16_f32 v40, v40, v42
	ds_write_b16 v216, v40
	ds_write_b16_d16_hi v217, v40
	v_lshlrev_b32_e32 v36, 16, v67
	v_lshlrev_b32_e32 v38, 16, v66
	v_add_f32_e32 v36, v239, v36
	v_add_f32_e32 v38, v240, v38
	v_and_b32_e32 v37, 0xffff0000, v67
	v_and_b32_e32 v39, 0xffff0000, v66
	v_mul_f32_e32 v36, v36, v37
	v_mul_f32_e32 v38, v38, v39
	v_cvt_pk_bf16_f32 v36, v36, v38
	ds_write_b16 v218, v36
	ds_write_b16_d16_hi v219, v36
	v_lshlrev_b32_e32 v40, 16, v64
	v_lshlrev_b32_e32 v42, 16, v48
	v_add_f32_e32 v40, v63, v40
	v_add_f32_e32 v42, v241, v42
	v_and_b32_e32 v41, 0xffff0000, v64
	v_and_b32_e32 v43, 0xffff0000, v48
	v_mul_f32_e32 v40, v40, v41
	v_mul_f32_e32 v42, v42, v43
	v_cvt_pk_bf16_f32 v40, v40, v42
	ds_write_b16 v220, v40
	ds_write_b16_d16_hi v221, v40
